# v38 + DFT item outputs staged through an XOR-swizzled LDS tile and stored as full 128-B lines (8 lanes per row) instead of 8-B pieces over 32 rows per instruction
# speedup vs baseline: 1.0095x; 1.0095x over previous
; __device__ __forceinline__ unsigned pk2(float lo, float hi) { f32x2_t v = {lo, hi}; bf16x2_t b = __builtin_convertvector(v, bf16x2_t); return __builtin_bit_cast(unsigned, b); }
; __device__ __forceinline__ void phase_prep(const Params& P, int l, unsigned char* lds) {
;     ...
; #pragma unroll
;             for (int q = 0; q < 4; ++q) {
;                 const int n = n0 + q;
;                 bf16_t* dC; bf16_t* dS;
;                 if (is_ctx) { bf16_t* z = (bf16_t*)(P.ws + WS_ZCT) + ((size_t)b * 256 + n) * 512 + t0 + t8; dC = z; dS = z + 256; }
;                 else { bf16_t* z = (bf16_t*)(P.ws + WS_ZT) + ((size_t)b * 256 + n) * 2048 + (t0 - CTX) + t8; dC = z; dS = z + 1024; }
;                 u32x4 o; o.x = pk2(aC[q][0], aC[q][1]); o.y = pk2(aC[q][2], aC[q][3]); o.z = pk2(aC[q][4], aC[q][5]); o.w = pk2(aC[q][6], aC[q][7]);
;                 *(u32x4*)dC = o;
;                 u32x4 s4; s4.x = pk2(aS[q][0], aS[q][1]); s4.y = pk2(aS[q][2], aS[q][3]); s4.z = pk2(aS[q][4], aS[q][5]); s4.w = pk2(aS[q][6], aS[q][7]);
;                 *(u32x4*)dS = s4;
;             }
.Ldft_nosp:
	s_nop 15
	s_nop 7
	s_barrier
	s_lshl_b32 s7, s15, 6
	v_add_u32_e32 v130, s7, v34
	v_lshlrev_b32_e32 v130, 7, v130
	v_lshl_add_u32 v130, v33, 3, v130
	v_and_b32_e32 v41, 7, v32
	s_lshl_b32 s7, s13, 2
	v_xor_b32_e32 v131, s7, v41
	v_xor_b32_e32 v132, 1, v131
	v_xor_b32_e32 v133, 2, v131
	v_xor_b32_e32 v134, 3, v131
	v_lshl_add_u32 v131, v131, 4, v130
	v_lshl_add_u32 v132, v132, 4, v130
	v_lshl_add_u32 v133, v133, 4, v130
	v_lshl_add_u32 v134, v134, 4, v130
	v_cvt_pk_bf16_f32 v126, v0, v1
	v_cvt_pk_bf16_f32 v127, v2, v3
	ds_write_b64 v131, v[126:127]
	v_cvt_pk_bf16_f32 v126, v4, v5
	v_cvt_pk_bf16_f32 v127, v6, v7
	ds_write_b64 v132, v[126:127]
	v_cvt_pk_bf16_f32 v126, v8, v9
	v_cvt_pk_bf16_f32 v127, v10, v11
	ds_write_b64 v133, v[126:127]
	v_cvt_pk_bf16_f32 v126, v12, v13
	v_cvt_pk_bf16_f32 v127, v14, v15
	ds_write_b64 v134, v[126:127]
	v_cvt_pk_bf16_f32 v126, v16, v17
	v_cvt_pk_bf16_f32 v127, v18, v19
	ds_write_b64 v131, v[126:127] offset:4096
	v_cvt_pk_bf16_f32 v126, v20, v21
	v_cvt_pk_bf16_f32 v127, v22, v23
	ds_write_b64 v132, v[126:127] offset:4096
	v_cvt_pk_bf16_f32 v126, v24, v25
	v_cvt_pk_bf16_f32 v127, v26, v27
	ds_write_b64 v133, v[126:127] offset:4096
	v_cvt_pk_bf16_f32 v126, v28, v29
	v_cvt_pk_bf16_f32 v127, v30, v31
	ds_write_b64 v134, v[126:127] offset:4096
	v_cvt_pk_bf16_f32 v126, v46, v47
	v_cvt_pk_bf16_f32 v127, v48, v49
	ds_write_b64 v131, v[126:127] offset:32768
	v_cvt_pk_bf16_f32 v126, v50, v51
	v_cvt_pk_bf16_f32 v127, v52, v53
	ds_write_b64 v132, v[126:127] offset:32768
	v_cvt_pk_bf16_f32 v126, v54, v55
	v_cvt_pk_bf16_f32 v127, v56, v57
	ds_write_b64 v133, v[126:127] offset:32768
	v_cvt_pk_bf16_f32 v126, v58, v59
	v_cvt_pk_bf16_f32 v127, v60, v61
	ds_write_b64 v134, v[126:127] offset:32768
	v_cvt_pk_bf16_f32 v126, v62, v63
	v_cvt_pk_bf16_f32 v127, v64, v65
	ds_write_b64 v131, v[126:127] offset:36864
	v_cvt_pk_bf16_f32 v126, v66, v67
	v_cvt_pk_bf16_f32 v127, v68, v69
	ds_write_b64 v132, v[126:127] offset:36864
	v_cvt_pk_bf16_f32 v126, v70, v71
	v_cvt_pk_bf16_f32 v127, v72, v73
	ds_write_b64 v133, v[126:127] offset:36864
	v_cvt_pk_bf16_f32 v126, v74, v75
	v_cvt_pk_bf16_f32 v127, v76, v77
	ds_write_b64 v134, v[126:127] offset:36864
	s_waitcnt lgkmcnt(0)
	s_barrier
	s_and_b64 vcc, exec, s[42:43]
	s_cbranch_vccz .Ldft_out_ctx
	s_lshl_b32 s7, s36, 8
	s_mul_i32 s7, s7, 4096
	s_sub_u32 s18, s64, 256
	s_lshl_b32 s18, s18, 1
	s_add_u32 s7, s7, s18
	s_add_u32 s40, s0, s7
	s_addc_u32 s41, s1, 0
	s_add_u32 s40, s40, 0x17e00000
	s_addc_u32 s41, s41, 0
	v_mov_b32_e32 v41, v44
	v_and_b32_e32 v42, 7, v41
	v_lshrrev_b32_e32 v43, 3, v41
	v_and_b32_e32 v120, 7, v43
	v_xor_b32_e32 v120, v120, v42
	v_lshlrev_b32_e32 v121, 7, v43
	v_lshl_add_u32 v121, v120, 4, v121
	ds_read_b128 v[136:139], v121
	v_and_b32_e32 v120, 0xff, v43
	v_lshrrev_b32_e32 v122, 8, v43
	v_mul_u32_u24_e32 v120, 4096, v120
	v_mul_u32_u24_e32 v122, 2048, v122
	v_lshl_add_u32 v120, v42, 4, v120
	v_add_u32_e32 v170, v120, v122
	v_add_u32_e32 v41, 512, v44
	v_and_b32_e32 v42, 7, v41
	v_lshrrev_b32_e32 v43, 3, v41
	v_and_b32_e32 v120, 7, v43
	v_xor_b32_e32 v120, v120, v42
	v_lshlrev_b32_e32 v121, 7, v43
	v_lshl_add_u32 v121, v120, 4, v121
	ds_read_b128 v[140:143], v121
	v_and_b32_e32 v120, 0xff, v43
	v_lshrrev_b32_e32 v122, 8, v43
	v_mul_u32_u24_e32 v120, 4096, v120
	v_mul_u32_u24_e32 v122, 2048, v122
	v_lshl_add_u32 v120, v42, 4, v120
	v_add_u32_e32 v171, v120, v122
	v_add_u32_e32 v41, 1024, v44
	v_and_b32_e32 v42, 7, v41
	v_lshrrev_b32_e32 v43, 3, v41
	v_and_b32_e32 v120, 7, v43
	v_xor_b32_e32 v120, v120, v42
	v_lshlrev_b32_e32 v121, 7, v43
	v_lshl_add_u32 v121, v120, 4, v121
	ds_read_b128 v[144:147], v121
	v_and_b32_e32 v120, 0xff, v43
	v_lshrrev_b32_e32 v122, 8, v43
	v_mul_u32_u24_e32 v120, 4096, v120
	v_mul_u32_u24_e32 v122, 2048, v122
	v_lshl_add_u32 v120, v42, 4, v120
	v_add_u32_e32 v172, v120, v122
	v_add_u32_e32 v41, 1536, v44
	v_and_b32_e32 v42, 7, v41
	v_lshrrev_b32_e32 v43, 3, v41
	v_and_b32_e32 v120, 7, v43
	v_xor_b32_e32 v120, v120, v42
	v_lshlrev_b32_e32 v121, 7, v43
	v_lshl_add_u32 v121, v120, 4, v121
	ds_read_b128 v[148:151], v121
	v_and_b32_e32 v120, 0xff, v43
	v_lshrrev_b32_e32 v122, 8, v43
	v_mul_u32_u24_e32 v120, 4096, v120
	v_mul_u32_u24_e32 v122, 2048, v122
	v_lshl_add_u32 v120, v42, 4, v120
	v_add_u32_e32 v173, v120, v122
	v_add_u32_e32 v41, 2048, v44
	v_and_b32_e32 v42, 7, v41
	v_lshrrev_b32_e32 v43, 3, v41
	v_and_b32_e32 v120, 7, v43
	v_xor_b32_e32 v120, v120, v42
	v_lshlrev_b32_e32 v121, 7, v43
	v_lshl_add_u32 v121, v120, 4, v121
	ds_read_b128 v[152:155], v121
	v_and_b32_e32 v120, 0xff, v43
	v_lshrrev_b32_e32 v122, 8, v43
	v_mul_u32_u24_e32 v120, 4096, v120
	v_mul_u32_u24_e32 v122, 2048, v122
	v_lshl_add_u32 v120, v42, 4, v120
	v_add_u32_e32 v174, v120, v122
	v_add_u32_e32 v41, 2560, v44
	v_and_b32_e32 v42, 7, v41
	v_lshrrev_b32_e32 v43, 3, v41
	v_and_b32_e32 v120, 7, v43
	v_xor_b32_e32 v120, v120, v42
	v_lshlrev_b32_e32 v121, 7, v43
	v_lshl_add_u32 v121, v120, 4, v121
	ds_read_b128 v[156:159], v121
	v_and_b32_e32 v120, 0xff, v43
	v_lshrrev_b32_e32 v122, 8, v43
	v_mul_u32_u24_e32 v120, 4096, v120
	v_mul_u32_u24_e32 v122, 2048, v122
	v_lshl_add_u32 v120, v42, 4, v120
	v_add_u32_e32 v175, v120, v122
	v_add_u32_e32 v41, 3072, v44
	v_and_b32_e32 v42, 7, v41
	v_lshrrev_b32_e32 v43, 3, v41
	v_and_b32_e32 v120, 7, v43
	v_xor_b32_e32 v120, v120, v42
	v_lshlrev_b32_e32 v121, 7, v43
	v_lshl_add_u32 v121, v120, 4, v121
	ds_read_b128 v[160:163], v121
	v_and_b32_e32 v120, 0xff, v43
	v_lshrrev_b32_e32 v122, 8, v43
	v_mul_u32_u24_e32 v120, 4096, v120
	v_mul_u32_u24_e32 v122, 2048, v122
	v_lshl_add_u32 v120, v42, 4, v120
	v_add_u32_e32 v176, v120, v122
	v_add_u32_e32 v41, 3584, v44
	v_and_b32_e32 v42, 7, v41
	v_lshrrev_b32_e32 v43, 3, v41
	v_and_b32_e32 v120, 7, v43
	v_xor_b32_e32 v120, v120, v42
	v_lshlrev_b32_e32 v121, 7, v43
	v_lshl_add_u32 v121, v120, 4, v121
	ds_read_b128 v[164:167], v121
	v_and_b32_e32 v120, 0xff, v43
	v_lshrrev_b32_e32 v122, 8, v43
	v_mul_u32_u24_e32 v120, 4096, v120
	v_mul_u32_u24_e32 v122, 2048, v122
	v_lshl_add_u32 v120, v42, 4, v120
	v_add_u32_e32 v177, v120, v122
	s_waitcnt lgkmcnt(7)
	global_store_dwordx4 v170, v[136:139], s[40:41]
	s_waitcnt lgkmcnt(6)
	global_store_dwordx4 v171, v[140:143], s[40:41]
	s_waitcnt lgkmcnt(5)
	global_store_dwordx4 v172, v[144:147], s[40:41]
	s_waitcnt lgkmcnt(4)
	global_store_dwordx4 v173, v[148:151], s[40:41]
	s_waitcnt lgkmcnt(3)
	global_store_dwordx4 v174, v[152:155], s[40:41]
	s_waitcnt lgkmcnt(2)
	global_store_dwordx4 v175, v[156:159], s[40:41]
	s_waitcnt lgkmcnt(1)
	global_store_dwordx4 v176, v[160:163], s[40:41]
	s_waitcnt lgkmcnt(0)
	global_store_dwordx4 v177, v[164:167], s[40:41]
	s_branch .Ldft_out_done
; __device__ __forceinline__ unsigned pk2(float lo, float hi) { f32x2_t v = {lo, hi}; bf16x2_t b = __builtin_convertvector(v, bf16x2_t); return __builtin_bit_cast(unsigned, b); }
; __device__ __forceinline__ void phase_prep(const Params& P, int l, unsigned char* lds) {
;     ...
; #pragma unroll
;             for (int q = 0; q < 4; ++q) {
;                 const int n = n0 + q;
;                 bf16_t* dC; bf16_t* dS;
;                 if (is_ctx) { bf16_t* z = (bf16_t*)(P.ws + WS_ZCT) + ((size_t)b * 256 + n) * 512 + t0 + t8; dC = z; dS = z + 256; }
;                 else { bf16_t* z = (bf16_t*)(P.ws + WS_ZT) + ((size_t)b * 256 + n) * 2048 + (t0 - CTX) + t8; dC = z; dS = z + 1024; }
;                 u32x4 o; o.x = pk2(aC[q][0], aC[q][1]); o.y = pk2(aC[q][2], aC[q][3]); o.z = pk2(aC[q][4], aC[q][5]); o.w = pk2(aC[q][6], aC[q][7]);
;                 *(u32x4*)dC = o;
;                 u32x4 s4; s4.x = pk2(aS[q][0], aS[q][1]); s4.y = pk2(aS[q][2], aS[q][3]); s4.z = pk2(aS[q][4], aS[q][5]); s4.w = pk2(aS[q][6], aS[q][7]);
;                 *(u32x4*)dS = s4;
;             }
.Ldft_out_ctx:
	s_lshl_b32 s7, s36, 8
	s_mul_i32 s7, s7, 1024
	s_sub_u32 s18, s64, 0
	s_lshl_b32 s18, s18, 1
	s_add_u32 s7, s7, s18
	s_add_u32 s40, s0, s7
	s_addc_u32 s41, s1, 0
	s_add_u32 s40, s40, 0x19e00000
	s_addc_u32 s41, s41, 0
	v_mov_b32_e32 v41, v44
	v_and_b32_e32 v42, 7, v41
	v_lshrrev_b32_e32 v43, 3, v41
	v_and_b32_e32 v120, 7, v43
	v_xor_b32_e32 v120, v120, v42
	v_lshlrev_b32_e32 v121, 7, v43
	v_lshl_add_u32 v121, v120, 4, v121
	ds_read_b128 v[136:139], v121
	v_and_b32_e32 v120, 0xff, v43
	v_lshrrev_b32_e32 v122, 8, v43
	v_mul_u32_u24_e32 v120, 1024, v120
	v_mul_u32_u24_e32 v122, 512, v122
	v_lshl_add_u32 v120, v42, 4, v120
	v_add_u32_e32 v170, v120, v122
	v_add_u32_e32 v41, 512, v44
	v_and_b32_e32 v42, 7, v41
	v_lshrrev_b32_e32 v43, 3, v41
	v_and_b32_e32 v120, 7, v43
	v_xor_b32_e32 v120, v120, v42
	v_lshlrev_b32_e32 v121, 7, v43
	v_lshl_add_u32 v121, v120, 4, v121
	ds_read_b128 v[140:143], v121
	v_and_b32_e32 v120, 0xff, v43
	v_lshrrev_b32_e32 v122, 8, v43
	v_mul_u32_u24_e32 v120, 1024, v120
	v_mul_u32_u24_e32 v122, 512, v122
	v_lshl_add_u32 v120, v42, 4, v120
	v_add_u32_e32 v171, v120, v122
	v_add_u32_e32 v41, 1024, v44
	v_and_b32_e32 v42, 7, v41
	v_lshrrev_b32_e32 v43, 3, v41
	v_and_b32_e32 v120, 7, v43
	v_xor_b32_e32 v120, v120, v42
	v_lshlrev_b32_e32 v121, 7, v43
	v_lshl_add_u32 v121, v120, 4, v121
	ds_read_b128 v[144:147], v121
	v_and_b32_e32 v120, 0xff, v43
	v_lshrrev_b32_e32 v122, 8, v43
	v_mul_u32_u24_e32 v120, 1024, v120
	v_mul_u32_u24_e32 v122, 512, v122
	v_lshl_add_u32 v120, v42, 4, v120
	v_add_u32_e32 v172, v120, v122
	v_add_u32_e32 v41, 1536, v44
	v_and_b32_e32 v42, 7, v41
	v_lshrrev_b32_e32 v43, 3, v41
	v_and_b32_e32 v120, 7, v43
	v_xor_b32_e32 v120, v120, v42
	v_lshlrev_b32_e32 v121, 7, v43
	v_lshl_add_u32 v121, v120, 4, v121
	ds_read_b128 v[148:151], v121
	v_and_b32_e32 v120, 0xff, v43
	v_lshrrev_b32_e32 v122, 8, v43
	v_mul_u32_u24_e32 v120, 1024, v120
	v_mul_u32_u24_e32 v122, 512, v122
	v_lshl_add_u32 v120, v42, 4, v120
	v_add_u32_e32 v173, v120, v122
	v_add_u32_e32 v41, 2048, v44
	v_and_b32_e32 v42, 7, v41
	v_lshrrev_b32_e32 v43, 3, v41
	v_and_b32_e32 v120, 7, v43
	v_xor_b32_e32 v120, v120, v42
	v_lshlrev_b32_e32 v121, 7, v43
	v_lshl_add_u32 v121, v120, 4, v121
	ds_read_b128 v[152:155], v121
	v_and_b32_e32 v120, 0xff, v43
	v_lshrrev_b32_e32 v122, 8, v43
	v_mul_u32_u24_e32 v120, 1024, v120
	v_mul_u32_u24_e32 v122, 512, v122
	v_lshl_add_u32 v120, v42, 4, v120
	v_add_u32_e32 v174, v120, v122
	v_add_u32_e32 v41, 2560, v44
	v_and_b32_e32 v42, 7, v41
	v_lshrrev_b32_e32 v43, 3, v41
	v_and_b32_e32 v120, 7, v43
	v_xor_b32_e32 v120, v120, v42
	v_lshlrev_b32_e32 v121, 7, v43
	v_lshl_add_u32 v121, v120, 4, v121
	ds_read_b128 v[156:159], v121
	v_and_b32_e32 v120, 0xff, v43
	v_lshrrev_b32_e32 v122, 8, v43
	v_mul_u32_u24_e32 v120, 1024, v120
	v_mul_u32_u24_e32 v122, 512, v122
	v_lshl_add_u32 v120, v42, 4, v120
	v_add_u32_e32 v175, v120, v122
	v_add_u32_e32 v41, 3072, v44
	v_and_b32_e32 v42, 7, v41
	v_lshrrev_b32_e32 v43, 3, v41
	v_and_b32_e32 v120, 7, v43
	v_xor_b32_e32 v120, v120, v42
	v_lshlrev_b32_e32 v121, 7, v43
	v_lshl_add_u32 v121, v120, 4, v121
	ds_read_b128 v[160:163], v121
	v_and_b32_e32 v120, 0xff, v43
	v_lshrrev_b32_e32 v122, 8, v43
	v_mul_u32_u24_e32 v120, 1024, v120
	v_mul_u32_u24_e32 v122, 512, v122
	v_lshl_add_u32 v120, v42, 4, v120
	v_add_u32_e32 v176, v120, v122
	v_add_u32_e32 v41, 3584, v44
	v_and_b32_e32 v42, 7, v41
	v_lshrrev_b32_e32 v43, 3, v41
	v_and_b32_e32 v120, 7, v43
	v_xor_b32_e32 v120, v120, v42
	v_lshlrev_b32_e32 v121, 7, v43
	v_lshl_add_u32 v121, v120, 4, v121
	ds_read_b128 v[164:167], v121
	v_and_b32_e32 v120, 0xff, v43
	v_lshrrev_b32_e32 v122, 8, v43
	v_mul_u32_u24_e32 v120, 1024, v120
	v_mul_u32_u24_e32 v122, 512, v122
	v_lshl_add_u32 v120, v42, 4, v120
	v_add_u32_e32 v177, v120, v122
	s_waitcnt lgkmcnt(7)
	global_store_dwordx4 v170, v[136:139], s[40:41]
	s_waitcnt lgkmcnt(6)
	global_store_dwordx4 v171, v[140:143], s[40:41]
	s_waitcnt lgkmcnt(5)
	global_store_dwordx4 v172, v[144:147], s[40:41]
	s_waitcnt lgkmcnt(4)
	global_store_dwordx4 v173, v[148:151], s[40:41]
	s_waitcnt lgkmcnt(3)
	global_store_dwordx4 v174, v[152:155], s[40:41]
	s_waitcnt lgkmcnt(2)
	global_store_dwordx4 v175, v[156:159], s[40:41]
	s_waitcnt lgkmcnt(1)
	global_store_dwordx4 v176, v[160:163], s[40:41]
	s_waitcnt lgkmcnt(0)
	global_store_dwordx4 v177, v[164:167], s[40:41]
